# P3 and P4 K-loop load segments also rewritten VALU-free (saddr LDS-DMA, single ds_read base), on top of P1/P5 saddr + team stagger + aligned P3 hook
# baseline (speedup 1.0000x reference)
.LBB0_581:
	s_mov_b64 s[10:11], 0x80
	s_and_b32 s3, s7, 3
	s_add_i32 m0, s31, 0x18000
	v_lshl_add_u64 v[10:11], v[10:11], 0, s[10:11]
	s_lshl_b32 s7, s12, 13
	s_lshl_b32 s13, s3, 12
	s_waitcnt vmcnt(2)
	s_barrier
	global_load_lds_dwordx4 v[10:11], off
	v_lshl_add_u64 v[8:9], v[8:9], 0, s[10:11]
	s_add_i32 m0, s31, 0x1a000
	s_add_i32 s47, s31, 0x8000
	s_add_i32 s48, s31, 0xa000
	global_load_lds_dwordx4 v[8:9], off
	v_lshl_add_u64 v[4:5], v[4:5], 0, s[10:11]
	s_mov_b32 m0, s47
	s_add_u32 s14, s4, 0x40080
	global_load_lds_dwordx4 v[4:5], off
	v_lshl_add_u64 v[4:5], v[6:7], 0, s[10:11]
	s_mov_b32 m0, s48
	s_addc_u32 s15, s5, 0
	global_load_lds_dwordx4 v[4:5], off
	s_add_i32 m0, s31, 0x1c000
	v_lshl_add_u64 v[4:5], s[14:15], 0, v[200:201]
	global_load_lds_dwordx4 v[4:5], off
	v_lshl_add_u64 v[4:5], s[14:15], 0, v[204:205]
	s_add_i32 m0, s31, 0x1e000
	s_cmpk_lt_u32 s6, 0x100
	global_load_lds_dwordx4 v[4:5], off
	v_bfe_u32 v5, v3, 4, 2
	v_and_b32_e32 v4, 15, v3
	v_lshlrev_b32_e32 v6, 3, v5
	v_lshlrev_b32_e32 v5, 4, v5
	v_lshlrev_b32_e32 v3, 2, v3
	v_lshl_or_b32 v212, s12, 6, v4
	v_lshl_or_b32 v4, v4, 6, v5
	v_and_b32_e32 v3, 32, v3
	v_bitop3_b32 v7, v4, s7, v3 bitop3:0xde
	v_bitop3_b32 v213, v4, s13, v3 bitop3:0xde
	v_add_u32_e32 v229, 0x10000, v213
	v_lshlrev_b32_e32 v3, 11, v212
	v_lshl_or_b32 v215, s3, 6, v3
	v_lshlrev_b32_e32 v3, 14, v12
	v_and_b32_e32 v3, 0xffff8000, v3
	v_lshl_add_u32 v3, v13, 11, v3
	v_and_b32_e32 v4, 1, v12
	v_lshl_or_b32 v3, v4, 6, v3
	v_readlane_b32 s6, v245, 0
	v_lshl_add_u32 v4, v14, 1, v3
	v_lshlrev_b32_e32 v3, 14, v15
	s_mov_b64 s[22:23], 0x40080
	s_cselect_b64 s[12:13], -1, 0
	s_bitcmp0_b32 s6, 7
	v_or_b32_e32 v216, 0x1800000, v5
	v_mov_b32_e32 v5, v2
	v_and_b32_e32 v3, 0xffff8000, v3
	s_cselect_b64 s[14:15], -1, 0
	s_bitcmp0_b32 s6, 9
	v_lshl_add_u64 v[206:207], v[4:5], 0, s[22:23]
	v_lshl_add_u32 v3, v16, 11, v3
	v_and_b32_e32 v4, 1, v15
	s_waitcnt vmcnt(6)
	s_cselect_b64 s[16:17], -1, 0
	s_bitcmp1_b32 s6, 8
	v_lshl_or_b32 v3, v4, 6, v3
	s_cselect_b64 s[18:19], -1, 0
	s_add_u32 s20, s84, 0x800000
	v_lshl_add_u32 v4, v17, 1, v3
	s_mov_b32 s49, 0x18000
	s_mov_b32 s50, 0x8000
	v_lshl_or_b32 v214, s3, 5, v6
	s_movk_i32 s51, 0x100
	s_addc_u32 s21, s85, 0
	v_lshl_add_u64 v[208:209], v[4:5], 0, s[22:23]
	s_mov_b32 s7, 0x20000
	s_brev_b32 s6, -2
	s_mov_b32 s52, 0x8100
	s_mov_b32 s53, 0x10100
	s_mov_b32 s54, 0x18100
	s_mov_b32 s55, 0x40000
	s_mov_b32 s56, 0x40100
	s_mov_b32 s57, 0x48000
	s_mov_b32 s58, 0x48100
	s_mov_b32 s59, 0x50000
	s_mov_b32 s60, 0x50100
	s_mov_b32 s61, 0x58000
	s_mov_b32 s62, 0x58100
	s_add_i32 s63, 0, 0x14000
	v_add_u32_e32 v217, 0, v7
	s_barrier
	s_branch .LBB0_584

.LBB0_587:
	s_add_u32 s4, s36, s38
	s_addc_u32 s5, s37, s39
	s_add_u32 s4, s4, 0x100
	s_addc_u32 s5, s5, 0
	s_add_u32 s72, s65, s38
	s_addc_u32 s73, s66, s39
	s_add_i32 s74, 0, 0x10000
	ds_read_b128 v[134:137], v229
	ds_read_b128 v[138:141], v229 offset:1024
	ds_read_b128 v[142:145], v229 offset:2048
	ds_read_b128 v[146:149], v229 offset:3072
	ds_read_b128 v[150:153], v229 offset:16384
	ds_read_b128 v[154:157], v229 offset:17408
	ds_read_b128 v[158:161], v229 offset:18432
	ds_read_b128 v[162:165], v229 offset:19456
	s_cmpk_eq_i32 s38, 0x700
	s_cselect_b32 s41, s3, s5
	s_cselect_b32 s40, s23, s4
	s_cselect_b32 s5, s25, s73
	s_cselect_b32 s4, s64, s72
	s_add_u32 s90, s36, s38
	s_addc_u32 s91, s37, s39
	s_add_i32 m0, s31, 0xc000
	ds_read_b128 v[166:169], v217
	ds_read_b128 v[176:179], v217 offset:1024
	ds_read_b128 v[180:183], v217 offset:2048
	ds_read_b128 v[184:187], v217 offset:3072
	ds_read_b128 v[188:191], v217 offset:4096
	ds_read_b128 v[192:195], v217 offset:5120
	ds_read_b128 v[218:221], v217 offset:6144
	ds_read_b128 v[222:225], v217 offset:7168
	global_load_lds_dwordx4 v206, s[90:91]
	s_add_i32 m0, s31, 0xe000
	s_nop 0
	global_load_lds_dwordx4 v208, s[90:91]
	s_waitcnt vmcnt(8)
	s_waitcnt lgkmcnt(0)
	s_barrier
	s_setprio 1
	v_mfma_f32_16x16x32_bf16 v[130:133], v[134:137], v[166:169], v[130:133]
	v_mfma_f32_16x16x32_bf16 v[126:129], v[142:145], v[166:169], v[126:129]
	v_mfma_f32_16x16x32_bf16 v[114:117], v[134:137], v[180:183], v[114:117]
	v_mfma_f32_16x16x32_bf16 v[110:113], v[142:145], v[180:183], v[110:113]
	v_mfma_f32_16x16x32_bf16 v[98:101], v[134:137], v[188:191], v[98:101]
	v_mfma_f32_16x16x32_bf16 v[94:97], v[142:145], v[188:191], v[94:97]
	v_mfma_f32_16x16x32_bf16 v[82:85], v[134:137], v[218:221], v[82:85]
	v_mfma_f32_16x16x32_bf16 v[78:81], v[142:145], v[218:221], v[78:81]
	v_mfma_f32_16x16x32_bf16 v[130:133], v[138:141], v[176:179], v[130:133]
	v_mfma_f32_16x16x32_bf16 v[126:129], v[146:149], v[176:179], v[126:129]
	v_mfma_f32_16x16x32_bf16 v[114:117], v[138:141], v[184:187], v[114:117]
	v_mfma_f32_16x16x32_bf16 v[110:113], v[146:149], v[184:187], v[110:113]
	v_mfma_f32_16x16x32_bf16 v[98:101], v[138:141], v[192:195], v[98:101]
	v_mfma_f32_16x16x32_bf16 v[94:97], v[146:149], v[192:195], v[94:97]
	v_mfma_f32_16x16x32_bf16 v[82:85], v[138:141], v[222:225], v[82:85]
	v_mfma_f32_16x16x32_bf16 v[78:81], v[146:149], v[222:225], v[78:81]
	v_mfma_f32_16x16x32_bf16 v[122:125], v[150:153], v[166:169], v[122:125]
	v_mfma_f32_16x16x32_bf16 v[118:121], v[158:161], v[166:169], v[118:121]
	v_mfma_f32_16x16x32_bf16 v[106:109], v[150:153], v[180:183], v[106:109]
	v_mfma_f32_16x16x32_bf16 v[102:105], v[158:161], v[180:183], v[102:105]
	v_mfma_f32_16x16x32_bf16 v[90:93], v[150:153], v[188:191], v[90:93]
	v_mfma_f32_16x16x32_bf16 v[86:89], v[158:161], v[188:191], v[86:89]
	v_mfma_f32_16x16x32_bf16 v[74:77], v[150:153], v[218:221], v[74:77]
	v_mfma_f32_16x16x32_bf16 v[70:73], v[158:161], v[218:221], v[70:73]
	v_mfma_f32_16x16x32_bf16 v[122:125], v[154:157], v[176:179], v[122:125]
	v_mfma_f32_16x16x32_bf16 v[118:121], v[162:165], v[176:179], v[118:121]
	v_mfma_f32_16x16x32_bf16 v[106:109], v[154:157], v[184:187], v[106:109]
	v_mfma_f32_16x16x32_bf16 v[102:105], v[162:165], v[184:187], v[102:105]
	s_setprio 2
	s_barrier
	v_mfma_f32_16x16x32_bf16 v[90:93], v[154:157], v[192:195], v[90:93]
	v_mfma_f32_16x16x32_bf16 v[86:89], v[162:165], v[192:195], v[86:89]
	v_mfma_f32_16x16x32_bf16 v[74:77], v[154:157], v[222:225], v[74:77]
	v_mfma_f32_16x16x32_bf16 v[70:73], v[162:165], v[222:225], v[70:73]
	s_setprio 0
	s_nop 0
	s_add_i32 s72, s74, s33
	s_mov_b32 m0, s72
	ds_read_b128 v[166:169], v217 offset:16384
	ds_read_b128 v[176:179], v217 offset:17408
	ds_read_b128 v[180:183], v217 offset:18432
	ds_read_b128 v[184:187], v217 offset:19456
	ds_read_b128 v[188:191], v217 offset:20480
	ds_read_b128 v[192:195], v217 offset:21504
	ds_read_b128 v[218:221], v217 offset:22528
	ds_read_b128 v[222:225], v217 offset:23552
	global_load_lds_dwordx4 v200, s[4:5]
	s_add_i32 m0, s72, 0x2000
	s_add_u32 s72, s4, 0x40000
	s_addc_u32 s73, s5, 0
	s_add_i32 s74, s63, s33
	global_load_lds_dwordx4 v204, s[4:5]
	s_mov_b32 m0, s74
	s_add_u32 s94, s40, 0x80
	s_addc_u32 s95, s41, 0
	global_load_lds_dwordx4 v200, s[72:73]
	s_add_i32 m0, s74, 0x2000
	s_nop 0
	global_load_lds_dwordx4 v204, s[72:73]
	s_mov_b32 m0, s31
	s_nop 0
	global_load_lds_dwordx4 v198, s[40:41]
	s_mov_b32 m0, s42
	s_nop 0
	global_load_lds_dwordx4 v202, s[40:41]
	s_waitcnt vmcnt(8)
	s_waitcnt lgkmcnt(0)
	s_barrier
	s_setprio 1
	v_mfma_f32_16x16x32_bf16 v[66:69], v[134:137], v[166:169], v[66:69]
	v_mfma_f32_16x16x32_bf16 v[62:65], v[142:145], v[166:169], v[62:65]
	v_mfma_f32_16x16x32_bf16 v[50:53], v[134:137], v[180:183], v[50:53]
	v_mfma_f32_16x16x32_bf16 v[46:49], v[142:145], v[180:183], v[46:49]
	v_mfma_f32_16x16x32_bf16 v[34:37], v[134:137], v[188:191], v[34:37]
	v_mfma_f32_16x16x32_bf16 v[30:33], v[142:145], v[188:191], v[30:33]
	v_mfma_f32_16x16x32_bf16 v[18:21], v[134:137], v[218:221], v[18:21]
	v_mfma_f32_16x16x32_bf16 v[14:17], v[142:145], v[218:221], v[14:17]
	v_mfma_f32_16x16x32_bf16 v[66:69], v[138:141], v[176:179], v[66:69]
	v_mfma_f32_16x16x32_bf16 v[62:65], v[146:149], v[176:179], v[62:65]
	v_mfma_f32_16x16x32_bf16 v[50:53], v[138:141], v[184:187], v[50:53]
	v_mfma_f32_16x16x32_bf16 v[46:49], v[146:149], v[184:187], v[46:49]
	v_mfma_f32_16x16x32_bf16 v[34:37], v[138:141], v[192:195], v[34:37]
	v_mfma_f32_16x16x32_bf16 v[30:33], v[146:149], v[192:195], v[30:33]
	v_mfma_f32_16x16x32_bf16 v[18:21], v[138:141], v[222:225], v[18:21]
	v_mfma_f32_16x16x32_bf16 v[14:17], v[146:149], v[222:225], v[14:17]
	v_mfma_f32_16x16x32_bf16 v[58:61], v[150:153], v[166:169], v[58:61]
	v_mfma_f32_16x16x32_bf16 v[54:57], v[158:161], v[166:169], v[54:57]
	v_mfma_f32_16x16x32_bf16 v[42:45], v[150:153], v[180:183], v[42:45]
	v_mfma_f32_16x16x32_bf16 v[38:41], v[158:161], v[180:183], v[38:41]
	v_mfma_f32_16x16x32_bf16 v[26:29], v[150:153], v[188:191], v[26:29]
	v_mfma_f32_16x16x32_bf16 v[22:25], v[158:161], v[188:191], v[22:25]
	v_mfma_f32_16x16x32_bf16 v[10:13], v[150:153], v[218:221], v[10:13]
	v_mfma_f32_16x16x32_bf16 v[4:7], v[158:161], v[218:221], v[6:9]
	v_mfma_f32_16x16x32_bf16 v[58:61], v[154:157], v[176:179], v[58:61]
	v_mfma_f32_16x16x32_bf16 v[54:57], v[162:165], v[176:179], v[54:57]
	v_mfma_f32_16x16x32_bf16 v[42:45], v[154:157], v[184:187], v[42:45]
	v_mfma_f32_16x16x32_bf16 v[38:41], v[162:165], v[184:187], v[38:41]
	s_setprio 2
	s_barrier
	v_mfma_f32_16x16x32_bf16 v[26:29], v[154:157], v[192:195], v[26:29]
	v_mfma_f32_16x16x32_bf16 v[22:25], v[162:165], v[192:195], v[22:25]
	v_mfma_f32_16x16x32_bf16 v[10:13], v[154:157], v[222:225], v[10:13]
	v_mfma_f32_16x16x32_bf16 v[4:7], v[162:165], v[222:225], v[4:7]
	s_setprio 0
	s_nop 0
	s_add_i32 s72, 0, 0x18000
	s_add_i32 s73, 0, 0x1c000
	ds_read_b128 v[134:137], v229 offset:32768
	ds_read_b128 v[138:141], v229 offset:33792
	ds_read_b128 v[142:145], v229 offset:34816
	ds_read_b128 v[146:149], v229 offset:35840
	ds_read_b128 v[150:153], v229 offset:49152
	ds_read_b128 v[154:157], v229 offset:50176
	ds_read_b128 v[158:161], v229 offset:51200
	ds_read_b128 v[162:165], v229 offset:52224
	s_add_u32 s40, s40, 0x40000
	s_addc_u32 s41, s41, 0
	s_mov_b32 m0, s43
	ds_read_b128 v[166:169], v217 offset:32768
	ds_read_b128 v[176:179], v217 offset:33792
	ds_read_b128 v[180:183], v217 offset:34816
	ds_read_b128 v[184:187], v217 offset:35840
	ds_read_b128 v[188:191], v217 offset:36864
	ds_read_b128 v[192:195], v217 offset:37888
	ds_read_b128 v[218:221], v217 offset:38912
	ds_read_b128 v[222:225], v217 offset:39936
	global_load_lds_dwordx4 v198, s[40:41]
	s_mov_b32 m0, s44
	s_nop 0
	global_load_lds_dwordx4 v202, s[40:41]
	s_waitcnt vmcnt(8)
	s_waitcnt lgkmcnt(0)
	s_barrier
	s_setprio 1
	v_mfma_f32_16x16x32_bf16 v[130:133], v[134:137], v[166:169], v[130:133]
	v_mfma_f32_16x16x32_bf16 v[126:129], v[142:145], v[166:169], v[126:129]
	v_mfma_f32_16x16x32_bf16 v[114:117], v[134:137], v[180:183], v[114:117]
	v_mfma_f32_16x16x32_bf16 v[110:113], v[142:145], v[180:183], v[110:113]
	v_mfma_f32_16x16x32_bf16 v[98:101], v[134:137], v[188:191], v[98:101]
	v_mfma_f32_16x16x32_bf16 v[94:97], v[142:145], v[188:191], v[94:97]
	v_mfma_f32_16x16x32_bf16 v[82:85], v[134:137], v[218:221], v[82:85]
	v_mfma_f32_16x16x32_bf16 v[78:81], v[142:145], v[218:221], v[78:81]
	v_mfma_f32_16x16x32_bf16 v[130:133], v[138:141], v[176:179], v[130:133]
	v_mfma_f32_16x16x32_bf16 v[126:129], v[146:149], v[176:179], v[126:129]
	v_mfma_f32_16x16x32_bf16 v[114:117], v[138:141], v[184:187], v[114:117]
	v_mfma_f32_16x16x32_bf16 v[110:113], v[146:149], v[184:187], v[110:113]
	v_mfma_f32_16x16x32_bf16 v[98:101], v[138:141], v[192:195], v[98:101]
	v_mfma_f32_16x16x32_bf16 v[94:97], v[146:149], v[192:195], v[94:97]
	v_mfma_f32_16x16x32_bf16 v[82:85], v[138:141], v[222:225], v[82:85]
	v_mfma_f32_16x16x32_bf16 v[78:81], v[146:149], v[222:225], v[78:81]
	v_mfma_f32_16x16x32_bf16 v[122:125], v[150:153], v[166:169], v[122:125]
	v_mfma_f32_16x16x32_bf16 v[118:121], v[158:161], v[166:169], v[118:121]
	v_mfma_f32_16x16x32_bf16 v[106:109], v[150:153], v[180:183], v[106:109]
	v_mfma_f32_16x16x32_bf16 v[102:105], v[158:161], v[180:183], v[102:105]
	v_mfma_f32_16x16x32_bf16 v[90:93], v[150:153], v[188:191], v[90:93]
	v_mfma_f32_16x16x32_bf16 v[86:89], v[158:161], v[188:191], v[86:89]
	v_mfma_f32_16x16x32_bf16 v[74:77], v[150:153], v[218:221], v[74:77]
	v_mfma_f32_16x16x32_bf16 v[70:73], v[158:161], v[218:221], v[70:73]
	v_mfma_f32_16x16x32_bf16 v[122:125], v[154:157], v[176:179], v[122:125]
	v_mfma_f32_16x16x32_bf16 v[118:121], v[162:165], v[176:179], v[118:121]
	v_mfma_f32_16x16x32_bf16 v[106:109], v[154:157], v[184:187], v[106:109]
	v_mfma_f32_16x16x32_bf16 v[102:105], v[162:165], v[184:187], v[102:105]
	s_setprio 2
	s_barrier
	v_mfma_f32_16x16x32_bf16 v[90:93], v[154:157], v[192:195], v[90:93]
	v_mfma_f32_16x16x32_bf16 v[86:89], v[162:165], v[192:195], v[86:89]
	v_mfma_f32_16x16x32_bf16 v[74:77], v[154:157], v[222:225], v[74:77]
	v_mfma_f32_16x16x32_bf16 v[70:73], v[162:165], v[222:225], v[70:73]
	s_setprio 0
	s_nop 0
	s_add_i32 s40, s72, s33
	s_add_u32 s96, s4, 0x80
	s_addc_u32 s97, s5, 0
	s_mov_b32 m0, s40
	ds_read_b128 v[166:169], v217 offset:49152
	ds_read_b128 v[176:179], v217 offset:50176
	ds_read_b128 v[180:183], v217 offset:51200
	ds_read_b128 v[184:187], v217 offset:52224
	ds_read_b128 v[188:191], v217 offset:53248
	ds_read_b128 v[192:195], v217 offset:54272
	ds_read_b128 v[218:221], v217 offset:55296
	ds_read_b128 v[222:225], v217 offset:56320
	global_load_lds_dwordx4 v200, s[96:97]
	s_add_i32 m0, s40, 0x2000
	s_add_u32 s4, s4, 0x40080
	s_addc_u32 s5, s5, 0
	s_add_i32 s40, s73, s33
	global_load_lds_dwordx4 v204, s[96:97]
	s_mov_b32 m0, s40
	s_nop 0
	global_load_lds_dwordx4 v200, s[4:5]
	s_add_i32 m0, s40, 0x2000
	s_nop 0
	global_load_lds_dwordx4 v204, s[4:5]
	s_mov_b32 m0, s47
	s_nop 0
	global_load_lds_dwordx4 v198, s[94:95]
	s_mov_b32 m0, s48
	s_nop 0
	global_load_lds_dwordx4 v202, s[94:95]
	s_waitcnt vmcnt(8)
	s_waitcnt lgkmcnt(0)
	s_barrier
	s_setprio 1
	v_mfma_f32_16x16x32_bf16 v[66:69], v[134:137], v[166:169], v[66:69]
	v_mfma_f32_16x16x32_bf16 v[62:65], v[142:145], v[166:169], v[62:65]
	v_mfma_f32_16x16x32_bf16 v[50:53], v[134:137], v[180:183], v[50:53]
	v_mfma_f32_16x16x32_bf16 v[46:49], v[142:145], v[180:183], v[46:49]
	v_mfma_f32_16x16x32_bf16 v[34:37], v[134:137], v[188:191], v[34:37]
	v_mfma_f32_16x16x32_bf16 v[30:33], v[142:145], v[188:191], v[30:33]
	v_mfma_f32_16x16x32_bf16 v[18:21], v[134:137], v[218:221], v[18:21]
	v_mfma_f32_16x16x32_bf16 v[14:17], v[142:145], v[218:221], v[14:17]
	v_mfma_f32_16x16x32_bf16 v[66:69], v[138:141], v[176:179], v[66:69]
	v_mfma_f32_16x16x32_bf16 v[62:65], v[146:149], v[176:179], v[62:65]
	v_mfma_f32_16x16x32_bf16 v[50:53], v[138:141], v[184:187], v[50:53]
	v_mfma_f32_16x16x32_bf16 v[46:49], v[146:149], v[184:187], v[46:49]
	v_mfma_f32_16x16x32_bf16 v[34:37], v[138:141], v[192:195], v[34:37]
	v_mfma_f32_16x16x32_bf16 v[30:33], v[146:149], v[192:195], v[30:33]
	v_mfma_f32_16x16x32_bf16 v[18:21], v[138:141], v[222:225], v[18:21]
	v_mfma_f32_16x16x32_bf16 v[14:17], v[146:149], v[222:225], v[14:17]
	v_mfma_f32_16x16x32_bf16 v[58:61], v[150:153], v[166:169], v[58:61]
	v_mfma_f32_16x16x32_bf16 v[54:57], v[158:161], v[166:169], v[54:57]
	v_mfma_f32_16x16x32_bf16 v[42:45], v[150:153], v[180:183], v[42:45]
	v_mfma_f32_16x16x32_bf16 v[38:41], v[158:161], v[180:183], v[38:41]
	v_mfma_f32_16x16x32_bf16 v[26:29], v[150:153], v[188:191], v[26:29]
	v_mfma_f32_16x16x32_bf16 v[22:25], v[158:161], v[188:191], v[22:25]
	v_mfma_f32_16x16x32_bf16 v[8:11], v[150:153], v[218:221], v[10:13]
	v_mfma_f32_16x16x32_bf16 v[4:7], v[158:161], v[218:221], v[4:7]
	v_mfma_f32_16x16x32_bf16 v[58:61], v[154:157], v[176:179], v[58:61]
	v_mfma_f32_16x16x32_bf16 v[54:57], v[162:165], v[176:179], v[54:57]
	v_mfma_f32_16x16x32_bf16 v[42:45], v[154:157], v[184:187], v[42:45]
	v_mfma_f32_16x16x32_bf16 v[38:41], v[162:165], v[184:187], v[38:41]
	s_setprio 2
	s_barrier
	v_mfma_f32_16x16x32_bf16 v[26:29], v[154:157], v[192:195], v[26:29]
	v_mfma_f32_16x16x32_bf16 v[22:25], v[162:165], v[192:195], v[22:25]
	v_mfma_f32_16x16x32_bf16 v[10:13], v[154:157], v[222:225], v[8:11]
	v_mfma_f32_16x16x32_bf16 v[6:9], v[162:165], v[222:225], v[4:7]
	s_setprio 0
	s_nop 0
	s_add_i32 s67, s67, 2
	s_add_u32 s38, s38, 0x100
	s_addc_u32 s39, s39, 0
	s_cmp_gt_u32 s67, 13
	s_cbranch_scc1 .LBB0_590

.LBB0_760:
	ds_read_b128 v[114:117], v232
	ds_read_b128 v[118:121], v232 offset:1024
	ds_read_b128 v[130:133], v232 offset:2048
	ds_read_b128 v[138:141], v232 offset:3072
	ds_read_b128 v[146:149], v233
	ds_read_b128 v[150:153], v233 offset:1024
	ds_read_b128 v[154:157], v233 offset:2048
	ds_read_b128 v[158:161], v233 offset:3072
	s_add_u32 s30, s28, 0xfffc0080
	s_addc_u32 s31, s29, -1
	s_cmp_eq_u32 s47, 12
	s_cselect_b32 s35, s3, s31
	s_cselect_b32 s34, s17, s30
	s_cselect_b32 s31, s19, s46
	s_cselect_b32 s30, s27, s45
	s_add_i32 m0, s36, 0xc000
	ds_read_b128 v[162:165], v234
	ds_read_b128 v[166:169], v234 offset:1024
	ds_read_b128 v[170:173], v234 offset:2048
	ds_read_b128 v[174:177], v234 offset:3072
	ds_read_b128 v[178:181], v234 offset:4096
	ds_read_b128 v[182:185], v234 offset:5120
	ds_read_b128 v[186:189], v234 offset:6144
	ds_read_b128 v[190:193], v234 offset:7168
	global_load_lds_dwordx4 v202, s[28:29]
	s_add_i32 m0, s36, 0xe000
	s_nop 0
	global_load_lds_dwordx4 v204, s[28:29]
	s_waitcnt vmcnt(8)
	s_waitcnt lgkmcnt(0)
	s_barrier
	s_setprio 1
	v_mfma_f32_16x16x32_bf16 v[142:145], v[114:117], v[162:165], v[142:145]
	v_mfma_f32_16x16x32_bf16 v[134:137], v[130:133], v[162:165], v[134:137]
	v_mfma_f32_16x16x32_bf16 v[110:113], v[114:117], v[170:173], v[110:113]
	v_mfma_f32_16x16x32_bf16 v[106:109], v[130:133], v[170:173], v[106:109]
	v_mfma_f32_16x16x32_bf16 v[94:97], v[114:117], v[178:181], v[94:97]
	v_mfma_f32_16x16x32_bf16 v[90:93], v[130:133], v[178:181], v[90:93]
	v_mfma_f32_16x16x32_bf16 v[78:81], v[114:117], v[186:189], v[78:81]
	v_mfma_f32_16x16x32_bf16 v[74:77], v[130:133], v[186:189], v[74:77]
	v_mfma_f32_16x16x32_bf16 v[142:145], v[118:121], v[166:169], v[142:145]
	v_mfma_f32_16x16x32_bf16 v[134:137], v[138:141], v[166:169], v[134:137]
	v_mfma_f32_16x16x32_bf16 v[110:113], v[118:121], v[174:177], v[110:113]
	v_mfma_f32_16x16x32_bf16 v[106:109], v[138:141], v[174:177], v[106:109]
	v_mfma_f32_16x16x32_bf16 v[94:97], v[118:121], v[182:185], v[94:97]
	v_mfma_f32_16x16x32_bf16 v[90:93], v[138:141], v[182:185], v[90:93]
	v_mfma_f32_16x16x32_bf16 v[78:81], v[118:121], v[190:193], v[78:81]
	v_mfma_f32_16x16x32_bf16 v[74:77], v[138:141], v[190:193], v[74:77]
	v_mfma_f32_16x16x32_bf16 v[126:129], v[146:149], v[162:165], v[126:129]
	v_mfma_f32_16x16x32_bf16 v[122:125], v[154:157], v[162:165], v[122:125]
	v_mfma_f32_16x16x32_bf16 v[102:105], v[146:149], v[170:173], v[102:105]
	v_mfma_f32_16x16x32_bf16 v[98:101], v[154:157], v[170:173], v[98:101]
	v_mfma_f32_16x16x32_bf16 v[86:89], v[146:149], v[178:181], v[86:89]
	v_mfma_f32_16x16x32_bf16 v[82:85], v[154:157], v[178:181], v[82:85]
	v_mfma_f32_16x16x32_bf16 v[70:73], v[146:149], v[186:189], v[70:73]
	v_mfma_f32_16x16x32_bf16 v[66:69], v[154:157], v[186:189], v[66:69]
	v_mfma_f32_16x16x32_bf16 v[126:129], v[150:153], v[166:169], v[126:129]
	v_mfma_f32_16x16x32_bf16 v[122:125], v[158:161], v[166:169], v[122:125]
	v_mfma_f32_16x16x32_bf16 v[102:105], v[150:153], v[174:177], v[102:105]
	v_mfma_f32_16x16x32_bf16 v[98:101], v[158:161], v[174:177], v[98:101]
	s_setprio 2
	s_barrier
	v_mfma_f32_16x16x32_bf16 v[86:89], v[150:153], v[182:185], v[86:89]
	v_mfma_f32_16x16x32_bf16 v[82:85], v[158:161], v[182:185], v[82:85]
	v_mfma_f32_16x16x32_bf16 v[70:73], v[150:153], v[190:193], v[70:73]
	v_mfma_f32_16x16x32_bf16 v[66:69], v[158:161], v[190:193], v[66:69]
	s_setprio 0
	s_nop 0
	s_add_i32 s48, s43, s33
	s_mov_b32 m0, s48
	ds_read_b128 v[162:165], v234 offset:16384
	ds_read_b128 v[166:169], v234 offset:17408
	ds_read_b128 v[170:173], v234 offset:18432
	ds_read_b128 v[174:177], v234 offset:19456
	ds_read_b128 v[178:181], v234 offset:20480
	ds_read_b128 v[182:185], v234 offset:21504
	ds_read_b128 v[186:189], v234 offset:22528
	ds_read_b128 v[190:193], v234 offset:23552
	global_load_lds_dwordx4 v196, s[30:31]
	s_add_i32 m0, s48, 0x2000
	s_add_u32 s48, s30, 0x40000
	s_addc_u32 s49, s31, 0
	s_add_i32 s50, s44, s33
	global_load_lds_dwordx4 v200, s[30:31]
	s_mov_b32 m0, s50
	s_add_u32 s94, s34, 0x80
	s_addc_u32 s95, s35, 0
	global_load_lds_dwordx4 v196, s[48:49]
	s_add_i32 m0, s50, 0x2000
	s_nop 0
	global_load_lds_dwordx4 v200, s[48:49]
	s_mov_b32 m0, s36
	s_nop 0
	global_load_lds_dwordx4 v194, s[34:35]
	s_mov_b32 m0, s37
	s_nop 0
	global_load_lds_dwordx4 v198, s[34:35]
	s_waitcnt vmcnt(8)
	s_waitcnt lgkmcnt(0)
	s_barrier
	s_setprio 1
	v_mfma_f32_16x16x32_bf16 v[62:65], v[114:117], v[162:165], v[62:65]
	v_mfma_f32_16x16x32_bf16 v[58:61], v[130:133], v[162:165], v[58:61]
	v_mfma_f32_16x16x32_bf16 v[46:49], v[114:117], v[170:173], v[46:49]
	v_mfma_f32_16x16x32_bf16 v[42:45], v[130:133], v[170:173], v[42:45]
	v_mfma_f32_16x16x32_bf16 v[30:33], v[114:117], v[178:181], v[30:33]
	v_mfma_f32_16x16x32_bf16 v[26:29], v[130:133], v[178:181], v[26:29]
	v_mfma_f32_16x16x32_bf16 v[14:17], v[114:117], v[186:189], v[14:17]
	v_mfma_f32_16x16x32_bf16 v[10:13], v[130:133], v[186:189], v[10:13]
	v_mfma_f32_16x16x32_bf16 v[62:65], v[118:121], v[166:169], v[62:65]
	v_mfma_f32_16x16x32_bf16 v[58:61], v[138:141], v[166:169], v[58:61]
	v_mfma_f32_16x16x32_bf16 v[46:49], v[118:121], v[174:177], v[46:49]
	v_mfma_f32_16x16x32_bf16 v[42:45], v[138:141], v[174:177], v[42:45]
	v_mfma_f32_16x16x32_bf16 v[30:33], v[118:121], v[182:185], v[30:33]
	v_mfma_f32_16x16x32_bf16 v[26:29], v[138:141], v[182:185], v[26:29]
	v_mfma_f32_16x16x32_bf16 v[14:17], v[118:121], v[190:193], v[14:17]
	v_mfma_f32_16x16x32_bf16 v[10:13], v[138:141], v[190:193], v[10:13]
	v_mfma_f32_16x16x32_bf16 v[54:57], v[146:149], v[162:165], v[54:57]
	v_mfma_f32_16x16x32_bf16 v[50:53], v[154:157], v[162:165], v[50:53]
	v_mfma_f32_16x16x32_bf16 v[38:41], v[146:149], v[170:173], v[38:41]
	v_mfma_f32_16x16x32_bf16 v[34:37], v[154:157], v[170:173], v[34:37]
	v_mfma_f32_16x16x32_bf16 v[22:25], v[146:149], v[178:181], v[22:25]
	v_mfma_f32_16x16x32_bf16 v[18:21], v[154:157], v[178:181], v[18:21]
	v_mfma_f32_16x16x32_bf16 v[6:9], v[146:149], v[186:189], v[6:9]
	v_mfma_f32_16x16x32_bf16 v[2:5], v[154:157], v[186:189], v[2:5]
	v_mfma_f32_16x16x32_bf16 v[54:57], v[150:153], v[166:169], v[54:57]
	v_mfma_f32_16x16x32_bf16 v[50:53], v[158:161], v[166:169], v[50:53]
	v_mfma_f32_16x16x32_bf16 v[38:41], v[150:153], v[174:177], v[38:41]
	v_mfma_f32_16x16x32_bf16 v[34:37], v[158:161], v[174:177], v[34:37]
	s_setprio 2
	s_barrier
	v_mfma_f32_16x16x32_bf16 v[22:25], v[150:153], v[182:185], v[22:25]
	v_mfma_f32_16x16x32_bf16 v[18:21], v[158:161], v[182:185], v[18:21]
	v_mfma_f32_16x16x32_bf16 v[6:9], v[150:153], v[190:193], v[6:9]
	v_mfma_f32_16x16x32_bf16 v[2:5], v[158:161], v[190:193], v[2:5]
	s_setprio 0
	s_nop 0
	s_add_i32 s48, 0, 0x18000
	s_add_i32 s49, 0, 0x1c000
	ds_read_b128 v[114:117], v232 offset:32768
	ds_read_b128 v[118:121], v232 offset:33792
	ds_read_b128 v[130:133], v232 offset:34816
	ds_read_b128 v[138:141], v232 offset:35840
	ds_read_b128 v[146:149], v233 offset:32768
	ds_read_b128 v[150:153], v233 offset:33792
	ds_read_b128 v[154:157], v233 offset:34816
	ds_read_b128 v[158:161], v233 offset:35840
	s_add_u32 s34, s34, 0x40000
	s_addc_u32 s35, s35, 0
	s_mov_b32 m0, s38
	ds_read_b128 v[162:165], v234 offset:32768
	ds_read_b128 v[166:169], v234 offset:33792
	ds_read_b128 v[170:173], v234 offset:34816
	ds_read_b128 v[174:177], v234 offset:35840
	ds_read_b128 v[178:181], v234 offset:36864
	ds_read_b128 v[182:185], v234 offset:37888
	ds_read_b128 v[186:189], v234 offset:38912
	ds_read_b128 v[190:193], v234 offset:39936
	global_load_lds_dwordx4 v194, s[34:35]
	s_mov_b32 m0, s39
	s_nop 0
	global_load_lds_dwordx4 v198, s[34:35]
	s_waitcnt vmcnt(8)
	s_waitcnt lgkmcnt(0)
	s_barrier
	s_setprio 1
	v_mfma_f32_16x16x32_bf16 v[142:145], v[114:117], v[162:165], v[142:145]
	v_mfma_f32_16x16x32_bf16 v[134:137], v[130:133], v[162:165], v[134:137]
	v_mfma_f32_16x16x32_bf16 v[110:113], v[114:117], v[170:173], v[110:113]
	v_mfma_f32_16x16x32_bf16 v[106:109], v[130:133], v[170:173], v[106:109]
	v_mfma_f32_16x16x32_bf16 v[94:97], v[114:117], v[178:181], v[94:97]
	v_mfma_f32_16x16x32_bf16 v[90:93], v[130:133], v[178:181], v[90:93]
	v_mfma_f32_16x16x32_bf16 v[78:81], v[114:117], v[186:189], v[78:81]
	v_mfma_f32_16x16x32_bf16 v[74:77], v[130:133], v[186:189], v[74:77]
	v_mfma_f32_16x16x32_bf16 v[142:145], v[118:121], v[166:169], v[142:145]
	v_mfma_f32_16x16x32_bf16 v[134:137], v[138:141], v[166:169], v[134:137]
	v_mfma_f32_16x16x32_bf16 v[110:113], v[118:121], v[174:177], v[110:113]
	v_mfma_f32_16x16x32_bf16 v[106:109], v[138:141], v[174:177], v[106:109]
	v_mfma_f32_16x16x32_bf16 v[94:97], v[118:121], v[182:185], v[94:97]
	v_mfma_f32_16x16x32_bf16 v[90:93], v[138:141], v[182:185], v[90:93]
	v_mfma_f32_16x16x32_bf16 v[78:81], v[118:121], v[190:193], v[78:81]
	v_mfma_f32_16x16x32_bf16 v[74:77], v[138:141], v[190:193], v[74:77]
	v_mfma_f32_16x16x32_bf16 v[126:129], v[146:149], v[162:165], v[126:129]
	v_mfma_f32_16x16x32_bf16 v[122:125], v[154:157], v[162:165], v[122:125]
	v_mfma_f32_16x16x32_bf16 v[102:105], v[146:149], v[170:173], v[102:105]
	v_mfma_f32_16x16x32_bf16 v[98:101], v[154:157], v[170:173], v[98:101]
	v_mfma_f32_16x16x32_bf16 v[86:89], v[146:149], v[178:181], v[86:89]
	v_mfma_f32_16x16x32_bf16 v[82:85], v[154:157], v[178:181], v[82:85]
	v_mfma_f32_16x16x32_bf16 v[70:73], v[146:149], v[186:189], v[70:73]
	v_mfma_f32_16x16x32_bf16 v[66:69], v[154:157], v[186:189], v[66:69]
	v_mfma_f32_16x16x32_bf16 v[126:129], v[150:153], v[166:169], v[126:129]
	v_mfma_f32_16x16x32_bf16 v[122:125], v[158:161], v[166:169], v[122:125]
	v_mfma_f32_16x16x32_bf16 v[102:105], v[150:153], v[174:177], v[102:105]
	v_mfma_f32_16x16x32_bf16 v[98:101], v[158:161], v[174:177], v[98:101]
	s_setprio 2
	s_barrier
	v_mfma_f32_16x16x32_bf16 v[86:89], v[150:153], v[182:185], v[86:89]
	v_mfma_f32_16x16x32_bf16 v[82:85], v[158:161], v[182:185], v[82:85]
	v_mfma_f32_16x16x32_bf16 v[70:73], v[150:153], v[190:193], v[70:73]
	v_mfma_f32_16x16x32_bf16 v[66:69], v[158:161], v[190:193], v[66:69]
	s_setprio 0
	s_nop 0
	s_add_i32 s34, s48, s33
	s_add_u32 s96, s30, 0x80
	s_addc_u32 s97, s31, 0
	s_mov_b32 m0, s34
	ds_read_b128 v[162:165], v234 offset:49152
	ds_read_b128 v[166:169], v234 offset:50176
	ds_read_b128 v[170:173], v234 offset:51200
	ds_read_b128 v[174:177], v234 offset:52224
	ds_read_b128 v[178:181], v234 offset:53248
	ds_read_b128 v[182:185], v234 offset:54272
	ds_read_b128 v[186:189], v234 offset:55296
	ds_read_b128 v[190:193], v234 offset:56320
	global_load_lds_dwordx4 v196, s[96:97]
	s_add_i32 m0, s34, 0x2000
	s_add_u32 s30, s30, 0x40080
	s_addc_u32 s31, s31, 0
	s_add_i32 s34, s49, s33
	global_load_lds_dwordx4 v200, s[96:97]
	s_mov_b32 m0, s34
	s_nop 0
	global_load_lds_dwordx4 v196, s[30:31]
	s_add_i32 m0, s34, 0x2000
	s_nop 0
	global_load_lds_dwordx4 v200, s[30:31]
	s_mov_b32 m0, s40
	s_nop 0
	global_load_lds_dwordx4 v194, s[94:95]
	s_mov_b32 m0, s41
	s_nop 0
	global_load_lds_dwordx4 v198, s[94:95]
	s_waitcnt vmcnt(8)
	s_waitcnt lgkmcnt(0)
	s_barrier
	s_setprio 1
	v_mfma_f32_16x16x32_bf16 v[62:65], v[114:117], v[162:165], v[62:65]
	v_mfma_f32_16x16x32_bf16 v[58:61], v[130:133], v[162:165], v[58:61]
	v_mfma_f32_16x16x32_bf16 v[46:49], v[114:117], v[170:173], v[46:49]
	v_mfma_f32_16x16x32_bf16 v[42:45], v[130:133], v[170:173], v[42:45]
	v_mfma_f32_16x16x32_bf16 v[30:33], v[114:117], v[178:181], v[30:33]
	v_mfma_f32_16x16x32_bf16 v[26:29], v[130:133], v[178:181], v[26:29]
	v_mfma_f32_16x16x32_bf16 v[14:17], v[114:117], v[186:189], v[14:17]
	v_mfma_f32_16x16x32_bf16 v[10:13], v[130:133], v[186:189], v[10:13]
	v_mfma_f32_16x16x32_bf16 v[62:65], v[118:121], v[166:169], v[62:65]
	v_mfma_f32_16x16x32_bf16 v[58:61], v[138:141], v[166:169], v[58:61]
	v_mfma_f32_16x16x32_bf16 v[46:49], v[118:121], v[174:177], v[46:49]
	v_mfma_f32_16x16x32_bf16 v[42:45], v[138:141], v[174:177], v[42:45]
	v_mfma_f32_16x16x32_bf16 v[30:33], v[118:121], v[182:185], v[30:33]
	v_mfma_f32_16x16x32_bf16 v[26:29], v[138:141], v[182:185], v[26:29]
	v_mfma_f32_16x16x32_bf16 v[14:17], v[118:121], v[190:193], v[14:17]
	v_mfma_f32_16x16x32_bf16 v[10:13], v[138:141], v[190:193], v[10:13]
	v_mfma_f32_16x16x32_bf16 v[54:57], v[146:149], v[162:165], v[54:57]
	v_mfma_f32_16x16x32_bf16 v[50:53], v[154:157], v[162:165], v[50:53]
	v_mfma_f32_16x16x32_bf16 v[38:41], v[146:149], v[170:173], v[38:41]
	v_mfma_f32_16x16x32_bf16 v[34:37], v[154:157], v[170:173], v[34:37]
	v_mfma_f32_16x16x32_bf16 v[22:25], v[146:149], v[178:181], v[22:25]
	v_mfma_f32_16x16x32_bf16 v[18:21], v[154:157], v[178:181], v[18:21]
	v_mfma_f32_16x16x32_bf16 v[6:9], v[146:149], v[186:189], v[6:9]
	v_mfma_f32_16x16x32_bf16 v[2:5], v[154:157], v[186:189], v[2:5]
	v_mfma_f32_16x16x32_bf16 v[54:57], v[150:153], v[166:169], v[54:57]
	v_mfma_f32_16x16x32_bf16 v[50:53], v[158:161], v[166:169], v[50:53]
	v_mfma_f32_16x16x32_bf16 v[38:41], v[150:153], v[174:177], v[38:41]
	v_mfma_f32_16x16x32_bf16 v[34:37], v[158:161], v[174:177], v[34:37]
	s_setprio 2
	s_barrier
	v_mfma_f32_16x16x32_bf16 v[22:25], v[150:153], v[182:185], v[22:25]
	v_mfma_f32_16x16x32_bf16 v[18:21], v[158:161], v[182:185], v[18:21]
	v_mfma_f32_16x16x32_bf16 v[6:9], v[150:153], v[190:193], v[6:9]
	v_mfma_f32_16x16x32_bf16 v[2:5], v[158:161], v[190:193], v[2:5]
	s_setprio 0
	s_nop 0
	s_add_i32 s47, s47, 2
	s_add_u32 s28, s28, 0x100
	s_addc_u32 s29, s29, 0
	s_add_u32 s45, s45, 0x100
	s_addc_u32 s46, s46, 0
	s_cmp_gt_u32 s47, 13
	s_cbranch_scc0 .LBB0_760
	s_and_b64 vcc, exec, s[10:11]
	s_cbranch_vccz .LBB0_763
	s_barrier
